# attention: next item's Q rows requested before the end-of-unit barrier (the wave's own Q region is free once its loop ends), K/V tiles after it
# speedup vs baseline: 1.0062x; 1.0062x over previous
.LBB0_737:
	v_mov_b32_e32 v130, v210
	s_add_i32 s74, s74, 1
	v_ashrrev_i32_e32 v189, 31, v188
	v_lshl_add_u64 v[128:129], v[188:189], 0, s[46:47]
	v_lshlrev_b32_e32 v130, 2, v130
	v_lshlrev_b64 v[140:141], 11, v[128:129]
	v_lshl_or_b32 v140, s75, 1, v140
	v_ashrrev_i32_e32 v131, 31, v130
	v_lshl_add_u64 v[128:129], s[48:49], 0, v[140:141]
	v_lshlrev_b64 v[136:137], 1, v[130:131]
	v_lshl_add_u64 v[134:135], v[136:137], 1, v[128:129]
	v_lshlrev_b32_e32 v215, 3, v206
	global_load_dwordx2 v[138:139], v215, s[52:53]
	global_load_dwordx4 v[160:163], v[134:135], off
	global_load_dwordx4 v[164:167], v[134:135], off offset:32
	global_load_dwordx4 v[168:171], v[134:135], off offset:64
	global_load_dwordx4 v[172:175], v[134:135], off offset:96
	global_load_dwordx4 v[202:205], v[134:135], off offset:128
	global_load_dwordx4 v[244:247], v[134:135], off offset:160
	global_load_dwordx4 v[248:251], v[134:135], off offset:192
	global_load_dwordx4 v[252:255], v[134:135], off offset:224
	s_lshr_b32 s0, s87, 2
	s_add_i32 s0, s0, 0x8000
	v_add_u32_e32 v217, s0, v215
	v_lshl_add_u32 v219, v210, 4, s0
	s_lshr_b32 s1, s100, 30
	s_add_i32 s1, s1, 3
	s_cmp_lt_u32 s74, s1
	s_cbranch_scc0 .Lq_skip
	s_mul_i32 s0, s74, 6
	s_lshr_b32 s0, s100, s0
	s_and_b32 s1, s0, 7
	s_bfe_u32 s36, s0, 0x30003
	s_lshl_b32 s1, s1, 8
	s_lshr_b32 s0, s87, 6
	s_lshl_b32 s37, s36, 8
	s_add_i32 s0, s0, s37
	v_or_b32_e32 v148, s0, v209
	v_add_u32_e32 v148, s46, v148
	v_lshlrev_b32_e32 v148, 11, v148
	v_add_u32_e32 v148, s1, v148
	v_add_co_u32_e32 v132, vcc, v178, v148
	s_lshl_b32 s0, s87, 2
	v_addc_co_u32_e32 v133, vcc, 0, v179, vcc
	s_add_i32 s0, s0, 0x18000
	s_mov_b32 m0, s0
	s_nop 0
	global_load_lds_dwordx4 v[132:133], off
	s_add_i32 m0, s0, 992
	s_nop 0
	global_load_lds_dwordx4 v[132:133], off offset:32
	s_add_i32 m0, s0, 1984
	s_nop 0
	global_load_lds_dwordx4 v[132:133], off offset:64
	s_add_i32 m0, s0, 2976
	s_nop 0
	global_load_lds_dwordx4 v[132:133], off offset:96
	s_add_i32 m0, s0, 3968
	s_nop 0
	global_load_lds_dwordx4 v[132:133], off offset:128
	s_add_i32 m0, s0, 4960
	s_nop 0
	global_load_lds_dwordx4 v[132:133], off offset:160
	s_add_i32 m0, s0, 5952
	s_nop 0
	global_load_lds_dwordx4 v[132:133], off offset:192
	s_add_i32 m0, s0, 6944
	s_nop 0
	global_load_lds_dwordx4 v[132:133], off offset:224
.Lq_skip:
	s_waitcnt lgkmcnt(0)
	s_barrier
	s_lshr_b32 s0, s100, 30
	s_add_i32 s0, s0, 3
	s_cmp_lt_u32 s74, s0
	s_cbranch_scc1 .Lpf_do
	s_waitcnt vmcnt(8)
	ds_write_b64 v217, v[138:139]
	s_waitcnt vmcnt(0)
	s_branch .Lpf_done
.Lpf_do:
	s_waitcnt vmcnt(16)
	ds_write_b64 v217, v[138:139]
	s_lshl_b32 s0, s46, 11
	s_add_i32 s1, s1, s0
	s_lshl_b32 s0, s36, 2
	s_or_b32 s0, s0, 3
	s_lshl_b32 s0, s0, 17
	s_add_i32 s0, s0, s1
	s_add_u32 s40, s42, s0
	s_addc_u32 s41, s43, 0
	s_add_u32 s66, s54, s0
	s_addc_u32 s67, s55, 0
	s_lshl_b32 s0, s36, 19
	s_or_b32 s0, s0, 0x40000
	s_add_i32 s36, s0, s1
	s_add_u32 s0, s42, s36
	s_addc_u32 s1, s43, 0
	s_add_u32 s36, s54, s36
	s_addc_u32 s37, s55, 0
	s_mov_b32 m0, s88
	s_nop 0
	global_load_lds_dwordx4 v176, s[40:41]
	s_mov_b32 m0, s89
	s_nop 0
	global_load_lds_dwordx4 v190, s[66:67]
	s_mov_b32 m0, s91
	s_nop 0
	global_load_lds_dwordx4 v192, s[40:41]
	s_mov_b32 m0, s92
	s_nop 0
	global_load_lds_dwordx4 v194, s[66:67]
	s_mov_b32 m0, s93
	s_nop 0
	global_load_lds_dwordx4 v176, s[0:1]
	s_mov_b32 m0, s94
	s_nop 0
	global_load_lds_dwordx4 v190, s[36:37]
	s_mov_b32 m0, s95
	s_nop 0
	global_load_lds_dwordx4 v192, s[0:1]
	s_mov_b32 m0, s96
	s_nop 0
	global_load_lds_dwordx4 v194, s[36:37]
